# v24 plus f32 divisions in scan staging and merge sigmoid via v_rcp_f32 + mul
# speedup vs baseline: 1.0165x; 1.0165x over previous
.LBB0_644:
	ds_read_b128 v[78:81], v180
	ds_read_b128 v[82:85], v180 offset:16
	s_waitcnt vmcnt(5)
	v_lshlrev_b32_e32 v88, 16, v22
	v_and_b32_e32 v89, 0xffff0000, v22
	v_lshlrev_b32_e32 v90, 16, v26
	v_and_b32_e32 v91, 0xffff0000, v26
	v_lshlrev_b32_e32 v86, 16, v18
	v_and_b32_e32 v87, 0xffff0000, v18
	v_pk_add_f32 v[88:89], v[88:89], v[90:91]
	v_lshlrev_b32_e32 v90, 16, v27
	v_pk_fma_f32 v[88:89], v[88:89], 0.5, v[86:87] op_sel_hi:[1,0,1] neg_lo:[0,0,1] neg_hi:[0,0,1]
	v_and_b32_e32 v91, 0xffff0000, v27
	s_waitcnt lgkmcnt(1)
	v_pk_fma_f32 v[78:79], v[88:89], v[78:79], v[86:87]
	v_lshlrev_b32_e32 v88, 16, v23
	v_and_b32_e32 v89, 0xffff0000, v23
	v_lshlrev_b32_e32 v86, 16, v19
	v_and_b32_e32 v87, 0xffff0000, v19
	v_pk_add_f32 v[88:89], v[88:89], v[90:91]
	s_waitcnt vmcnt(4)
	v_lshlrev_b32_e32 v90, 16, v39
	v_pk_fma_f32 v[88:89], v[88:89], 0.5, v[86:87] op_sel_hi:[1,0,1] neg_lo:[0,0,1] neg_hi:[0,0,1]
	v_and_b32_e32 v91, 0xffff0000, v39
	v_pk_fma_f32 v[80:81], v[88:89], v[80:81], v[86:87]
	ds_write_b128 v181, v[78:81]
	v_lshlrev_b32_e32 v80, 16, v24
	v_and_b32_e32 v81, 0xffff0000, v24
	v_lshlrev_b32_e32 v86, 16, v28
	v_and_b32_e32 v87, 0xffff0000, v28
	v_lshlrev_b32_e32 v78, 16, v20
	v_and_b32_e32 v79, 0xffff0000, v20
	v_pk_add_f32 v[80:81], v[80:81], v[86:87]
	v_lshlrev_b32_e32 v86, 16, v29
	v_pk_fma_f32 v[80:81], v[80:81], 0.5, v[78:79] op_sel_hi:[1,0,1] neg_lo:[0,0,1] neg_hi:[0,0,1]
	v_and_b32_e32 v87, 0xffff0000, v29
	s_waitcnt lgkmcnt(1)
	v_pk_fma_f32 v[78:79], v[80:81], v[82:83], v[78:79]
	v_lshlrev_b32_e32 v82, 16, v25
	v_and_b32_e32 v83, 0xffff0000, v25
	v_lshlrev_b32_e32 v80, 16, v21
	v_and_b32_e32 v81, 0xffff0000, v21
	v_pk_add_f32 v[82:83], v[82:83], v[86:87]
	v_lshlrev_b32_e32 v86, 16, v30
	v_pk_fma_f32 v[82:83], v[82:83], 0.5, v[80:81] op_sel_hi:[1,0,1] neg_lo:[0,0,1] neg_hi:[0,0,1]
	v_and_b32_e32 v87, 0xffff0000, v30
	v_pk_fma_f32 v[80:81], v[82:83], v[84:85], v[80:81]
	ds_write_b128 v181, v[78:81] offset:16
	ds_read_b128 v[78:81], v182
	v_lshlrev_b32_e32 v82, 16, v34
	v_and_b32_e32 v83, 0xffff0000, v34
	v_lshlrev_b32_e32 v84, 16, v38
	v_and_b32_e32 v85, 0xffff0000, v38
	v_pk_add_f32 v[82:83], v[82:83], v[84:85]
	s_waitcnt vmcnt(3)
	v_lshlrev_b32_e32 v98, 16, v47
	v_pk_fma_f32 v[88:89], v[82:83], 0.5, v[86:87] op_sel_hi:[1,0,1] neg_lo:[0,0,1] neg_hi:[0,0,1]
	ds_read_b128 v[82:85], v182 offset:16
	s_waitcnt lgkmcnt(1)
	v_pk_fma_f32 v[78:79], v[88:89], v[78:79], v[86:87]
	v_lshlrev_b32_e32 v88, 16, v35
	v_and_b32_e32 v89, 0xffff0000, v35
	v_lshlrev_b32_e32 v86, 16, v31
	v_and_b32_e32 v87, 0xffff0000, v31
	v_pk_add_f32 v[88:89], v[88:89], v[90:91]
	v_lshlrev_b32_e32 v90, 16, v42
	v_pk_fma_f32 v[88:89], v[88:89], 0.5, v[86:87] op_sel_hi:[1,0,1] neg_lo:[0,0,1] neg_hi:[0,0,1]
	v_and_b32_e32 v91, 0xffff0000, v42
	v_pk_fma_f32 v[80:81], v[88:89], v[80:81], v[86:87]
	ds_write_b128 v181, v[78:81] offset:8192
	v_lshlrev_b32_e32 v80, 16, v36
	v_and_b32_e32 v81, 0xffff0000, v36
	v_lshlrev_b32_e32 v86, 16, v40
	v_and_b32_e32 v87, 0xffff0000, v40
	v_lshlrev_b32_e32 v78, 16, v32
	v_and_b32_e32 v79, 0xffff0000, v32
	v_pk_add_f32 v[80:81], v[80:81], v[86:87]
	v_lshlrev_b32_e32 v86, 16, v41
	v_pk_fma_f32 v[80:81], v[80:81], 0.5, v[78:79] op_sel_hi:[1,0,1] neg_lo:[0,0,1] neg_hi:[0,0,1]
	v_and_b32_e32 v87, 0xffff0000, v41
	s_waitcnt lgkmcnt(1)
	v_pk_fma_f32 v[78:79], v[80:81], v[82:83], v[78:79]
	v_lshlrev_b32_e32 v82, 16, v37
	v_and_b32_e32 v83, 0xffff0000, v37
	v_lshlrev_b32_e32 v80, 16, v33
	v_and_b32_e32 v81, 0xffff0000, v33
	v_pk_add_f32 v[82:83], v[82:83], v[86:87]
	v_and_b32_e32 v99, 0xffff0000, v47
	v_pk_fma_f32 v[82:83], v[82:83], 0.5, v[80:81] op_sel_hi:[1,0,1] neg_lo:[0,0,1] neg_hi:[0,0,1]
	v_lshlrev_b32_e32 v100, 16, v51
	v_pk_fma_f32 v[80:81], v[82:83], v[84:85], v[80:81]
	ds_write_b128 v181, v[78:81] offset:8208
	ds_read_b128 v[78:81], v183
	v_lshlrev_b32_e32 v82, 16, v46
	v_and_b32_e32 v83, 0xffff0000, v46
	v_lshlrev_b32_e32 v84, 16, v50
	v_and_b32_e32 v85, 0xffff0000, v50
	v_pk_add_f32 v[86:87], v[82:83], v[84:85]
	ds_read_b128 v[82:85], v184
	v_pk_fma_f32 v[92:93], v[86:87], 0.5, v[90:91] op_sel_hi:[1,0,1] neg_lo:[0,0,1] neg_hi:[0,0,1]
	ds_read_b128 v[86:89], v183 offset:16
	s_waitcnt lgkmcnt(2)
	v_pk_fma_f32 v[78:79], v[92:93], v[78:79], v[90:91]
	v_and_b32_e32 v101, 0xffff0000, v51
	ds_read_b128 v[90:93], v184 offset:16
	s_waitcnt lgkmcnt(2)
	v_pk_mul_f32 v[94:95], v[78:79], v[82:83]
	v_lshlrev_b32_e32 v82, 16, v43
	v_and_b32_e32 v83, 0xffff0000, v43
	v_pk_add_f32 v[98:99], v[98:99], v[100:101]
	v_lshlrev_b32_e32 v102, 16, v52
	v_pk_fma_f32 v[98:99], v[98:99], 0.5, v[82:83] op_sel_hi:[1,0,1] neg_lo:[0,0,1] neg_hi:[0,0,1]
	v_and_b32_e32 v103, 0xffff0000, v52
	v_pk_fma_f32 v[80:81], v[98:99], v[80:81], v[82:83]
	v_lshlrev_b32_e32 v82, 16, v44
	v_pk_mul_f32 v[98:99], v[80:81], v[84:85]
	v_lshlrev_b32_e32 v84, 16, v48
	v_and_b32_e32 v85, 0xffff0000, v48
	v_and_b32_e32 v83, 0xffff0000, v44
	v_pk_add_f32 v[84:85], v[84:85], v[102:103]
	v_pk_mul_f32 v[96:97], v[94:95], v[94:95]
	v_pk_fma_f32 v[84:85], v[84:85], 0.5, v[82:83] op_sel_hi:[1,0,1] neg_lo:[0,0,1] neg_hi:[0,0,1]
	v_lshlrev_b32_e32 v102, 16, v49
	v_and_b32_e32 v103, 0xffff0000, v49
	v_lshlrev_b32_e32 v104, 16, v53
	v_and_b32_e32 v105, 0xffff0000, v53
	v_pk_mul_f32 v[100:101], v[98:99], v[98:99]
	s_waitcnt lgkmcnt(1)
	v_pk_fma_f32 v[82:83], v[84:85], v[86:87], v[82:83]
	v_lshlrev_b32_e32 v84, 16, v45
	v_and_b32_e32 v85, 0xffff0000, v45
	v_pk_add_f32 v[102:103], v[102:103], v[104:105]
	v_add_f32_e32 v1, v96, v97
	s_waitcnt lgkmcnt(0)
	v_pk_mul_f32 v[86:87], v[82:83], v[90:91]
	v_pk_fma_f32 v[102:103], v[102:103], 0.5, v[84:85] op_sel_hi:[1,0,1] neg_lo:[0,0,1] neg_hi:[0,0,1]
	v_add_f32_e32 v1, v1, v100
	v_pk_mul_f32 v[90:91], v[86:87], v[86:87]
	v_pk_fma_f32 v[84:85], v[102:103], v[88:89], v[84:85]
	v_add_f32_e32 v1, v1, v101
	v_pk_mul_f32 v[88:89], v[84:85], v[92:93]
	v_add_f32_e32 v1, v1, v90
	v_pk_mul_f32 v[92:93], v[88:89], v[88:89]
	v_add_f32_e32 v1, v1, v91
	v_add_f32_e32 v1, v1, v92
	v_add_f32_e32 v1, v1, v93
	s_mov_b32 s6, 0xf800000
	ds_write_b128 v181, v[78:81] offset:24576
	ds_write_b128 v181, v[82:85] offset:24592
	v_add_f32_dpp v1, v1, v1 quad_perm:[1,0,3,2] row_mask:0xf bank_mask:0xf bound_ctrl:1
	s_nop 1
	v_add_f32_dpp v1, v1, v1 quad_perm:[2,3,0,1] row_mask:0xf bank_mask:0xf bound_ctrl:1
	s_nop 1
	v_add_f32_dpp v1, v1, v1 row_half_mirror row_mask:0xf bank_mask:0xf bound_ctrl:1
	v_mul_f32_e32 v90, 0x4f800000, v1
	v_cmp_gt_f32_e32 vcc, s6, v1
	s_nop 1
	v_cndmask_b32_e32 v1, v1, v90, vcc
	v_sqrt_f32_e32 v90, v1
	s_nop 0
	v_add_u32_e32 v91, -1, v90
	v_fma_f32 v92, -v91, v90, v1
	v_cmp_ge_f32_e64 s[46:47], 0, v92
	v_add_u32_e32 v92, 1, v90
	s_nop 0
	v_cndmask_b32_e64 v91, v90, v91, s[46:47]
	v_fma_f32 v90, -v92, v90, v1
	v_cmp_lt_f32_e64 s[46:47], 0, v90
	s_nop 1
	v_cndmask_b32_e64 v90, v91, v92, s[46:47]
	v_mul_f32_e32 v91, 0x37800000, v90
	v_cndmask_b32_e32 v90, v90, v91, vcc
	v_cmp_class_f32_e32 vcc, v1, v237
	s_waitcnt vmcnt(2)
	v_and_b32_e32 v92, 0xffff0000, v57
	v_cndmask_b32_e32 v1, v90, v1, vcc
	v_max_f32_e32 v1, 0x2b8cbccc, v1
	s_nop 0
	v_rcp_f32_e32 v82, v1
	s_nop 0
	v_pk_mul_f32 v[78:79], v[94:95], v[82:83] op_sel_hi:[1,0]
	v_pk_mul_f32 v[80:81], v[98:99], v[82:83] op_sel_hi:[1,0]
	ds_write_b128 v181, v[78:81] offset:16384
	v_pk_mul_f32 v[78:79], v[86:87], v[82:83] op_sel_hi:[1,0]
	v_pk_mul_f32 v[80:81], v[88:89], v[82:83] op_sel_hi:[1,0]
	ds_write_b128 v181, v[78:81] offset:16400
	ds_read_b128 v[78:81], v185
	ds_read_b128 v[82:85], v185 offset:16
	v_lshlrev_b32_e32 v87, 16, v58
	v_lshlrev_b32_e32 v88, 16, v62
	v_lshlrev_b32_e32 v1, 16, v54
	v_add_f32_e32 v87, v88, v87
	v_fma_f32 v87, v87, 0.5, -v1
	s_waitcnt lgkmcnt(1)
	v_fmac_f32_e32 v1, v87, v78
	v_and_b32_e32 v78, 0xffff0000, v62
	v_and_b32_e32 v87, 0xffff0000, v58
	v_and_b32_e32 v86, 0xffff0000, v54
	v_add_f32_e32 v78, v78, v87
	v_fma_f32 v78, v78, 0.5, -v86
	v_fmac_f32_e32 v86, v78, v79
	v_lshlrev_b32_e32 v78, 16, v59
	v_lshlrev_b32_e32 v79, 16, v63
	v_lshlrev_b32_e32 v87, 16, v55
	v_add_f32_e32 v78, v79, v78
	v_fma_f32 v78, v78, 0.5, -v87
	v_fmac_f32_e32 v87, v78, v80
	v_and_b32_e32 v78, 0xffff0000, v63
	v_and_b32_e32 v79, 0xffff0000, v59
	v_and_b32_e32 v88, 0xffff0000, v55
	v_add_f32_e32 v78, v78, v79
	v_fma_f32 v78, v78, 0.5, -v88
	v_fmac_f32_e32 v88, v78, v81
	v_lshlrev_b32_e32 v78, 16, v60
	v_lshlrev_b32_e32 v79, 16, v64
	v_lshlrev_b32_e32 v89, 16, v56
	v_add_f32_e32 v78, v79, v78
	v_fma_f32 v78, v78, 0.5, -v89
	s_waitcnt lgkmcnt(0)
	v_fmac_f32_e32 v89, v78, v82
	v_and_b32_e32 v78, 0xffff0000, v64
	v_and_b32_e32 v79, 0xffff0000, v60
	v_and_b32_e32 v90, 0xffff0000, v56
	v_add_f32_e32 v78, v78, v79
	v_fma_f32 v78, v78, 0.5, -v90
	v_fmac_f32_e32 v90, v78, v83
	v_lshlrev_b32_e32 v78, 16, v61
	v_lshlrev_b32_e32 v79, 16, v65
	v_add_f32_e32 v1, v1, v1
	v_lshlrev_b32_e32 v91, 16, v57
	v_add_f32_e32 v78, v79, v78
	v_mul_f32_e32 v1, 0x3fb8aa3b, v1
	v_fma_f32 v80, v78, 0.5, -v91
	v_exp_f32_e32 v78, v1
	v_add_f32_e32 v1, v86, v86
	v_mul_f32_e32 v1, 0x3fb8aa3b, v1
	v_exp_f32_e32 v79, v1
	v_fmac_f32_e32 v91, v80, v84
	v_and_b32_e32 v1, 0xffff0000, v65
	v_and_b32_e32 v80, 0xffff0000, v61
	v_pk_add_f32 v[78:79], v[78:79], 1.0 op_sel_hi:[1,0]
	v_add_f32_e32 v1, v1, v80
	v_fma_f32 v1, v1, 0.5, -v92
	v_fmac_f32_e32 v92, v1, v85
	v_add_f32_e32 v80, v87, v87
	v_add_f32_e32 v81, v88, v88
	v_mul_f32_e32 v80, 0x3fb8aa3b, v80
	v_mul_f32_e32 v81, 0x3fb8aa3b, v81
	v_rcp_f32_e32 v1, v79
	s_nop 0
	v_mul_f32_e32 v79, 2.0, v1
	v_exp_f32_e32 v80, v80
	v_exp_f32_e32 v81, v81
	s_nop 4
	v_pk_add_f32 v[80:81], v[80:81], 1.0 op_sel_hi:[1,0]
	v_rcp_f32_e32 v1, v78
	s_nop 0
	v_mul_f32_e32 v78, 2.0, v1
	v_pk_add_f32 v[78:79], v[78:79], 1.0 op_sel_hi:[1,0] neg_lo:[1,0] neg_hi:[1,0]
	v_add_f32_e32 v82, v89, v89
	v_add_f32_e32 v83, v90, v90
	v_mul_f32_e32 v82, 0x3fb8aa3b, v82
	v_mul_f32_e32 v83, 0x3fb8aa3b, v83
	v_rcp_f32_e32 v1, v81
	s_nop 0
	v_mul_f32_e32 v81, 2.0, v1
	v_exp_f32_e32 v82, v82
	v_exp_f32_e32 v83, v83
	s_nop 4
	v_pk_add_f32 v[82:83], v[82:83], 1.0 op_sel_hi:[1,0]
	v_rcp_f32_e32 v1, v80
	s_nop 0
	v_mul_f32_e32 v80, 2.0, v1
	v_pk_add_f32 v[80:81], v[80:81], 1.0 op_sel_hi:[1,0] neg_lo:[1,0] neg_hi:[1,0]
	v_add_f32_e32 v84, v91, v91
	v_add_f32_e32 v85, v92, v92
	v_mul_f32_e32 v84, 0x3fb8aa3b, v84
	v_mul_f32_e32 v85, 0x3fb8aa3b, v85
	v_rcp_f32_e32 v1, v83
	s_nop 0
	v_mul_f32_e32 v83, 2.0, v1
	v_exp_f32_e32 v84, v84
	v_exp_f32_e32 v85, v85
	s_nop 4
	v_pk_add_f32 v[84:85], v[84:85], 1.0 op_sel_hi:[1,0]
	v_rcp_f32_e32 v1, v82
	s_nop 0
	v_mul_f32_e32 v82, 2.0, v1
	v_pk_add_f32 v[82:83], v[82:83], 1.0 op_sel_hi:[1,0] neg_lo:[1,0] neg_hi:[1,0]
	v_rcp_f32_e32 v1, v85
	s_nop 0
	v_mul_f32_e32 v85, 2.0, v1
	v_cvt_pk_bf16_f32 v78, v78, v79
	v_rcp_f32_e32 v1, v84
	s_nop 0
	v_mul_f32_e32 v84, 2.0, v1
	v_pk_add_f32 v[84:85], v[84:85], 1.0 op_sel_hi:[1,0] neg_lo:[1,0] neg_hi:[1,0]
	v_cvt_pk_bf16_f32 v79, v80, v81
	v_cvt_pk_bf16_f32 v80, v82, v83
	v_cvt_pk_bf16_f32 v81, v84, v85
	ds_write_b128 v186, v[78:81] offset:57856
	ds_read_b128 v[78:81], v187
	ds_read_b128 v[82:85], v187 offset:16
	s_waitcnt vmcnt(1)
	v_lshlrev_b32_e32 v88, 16, v70
	v_and_b32_e32 v89, 0xffff0000, v70
	v_lshlrev_b32_e32 v90, 16, v74
	v_and_b32_e32 v91, 0xffff0000, v74
	v_lshlrev_b32_e32 v86, 16, v66
	v_and_b32_e32 v87, 0xffff0000, v66
	v_pk_add_f32 v[88:89], v[88:89], v[90:91]
	v_lshlrev_b32_e32 v90, 16, v75
	v_pk_fma_f32 v[88:89], v[88:89], 0.5, v[86:87] op_sel_hi:[1,0,1] neg_lo:[0,0,1] neg_hi:[0,0,1]
	v_and_b32_e32 v91, 0xffff0000, v75
	s_waitcnt lgkmcnt(1)
	v_pk_fma_f32 v[78:79], v[88:89], v[78:79], v[86:87]
	v_lshlrev_b32_e32 v88, 16, v71
	v_and_b32_e32 v89, 0xffff0000, v71
	v_lshlrev_b32_e32 v86, 16, v67
	v_and_b32_e32 v87, 0xffff0000, v67
	v_pk_add_f32 v[88:89], v[88:89], v[90:91]
	v_lshlrev_b32_e32 v90, 16, v76
	v_pk_fma_f32 v[88:89], v[88:89], 0.5, v[86:87] op_sel_hi:[1,0,1] neg_lo:[0,0,1] neg_hi:[0,0,1]
	v_and_b32_e32 v91, 0xffff0000, v76
	v_pk_fma_f32 v[80:81], v[88:89], v[80:81], v[86:87]
	v_lshlrev_b32_e32 v88, 16, v72
	v_and_b32_e32 v89, 0xffff0000, v72
	v_lshlrev_b32_e32 v86, 16, v68
	v_and_b32_e32 v87, 0xffff0000, v68
	v_pk_add_f32 v[88:89], v[88:89], v[90:91]
	v_lshlrev_b32_e32 v90, 16, v77
	v_pk_fma_f32 v[88:89], v[88:89], 0.5, v[86:87] op_sel_hi:[1,0,1] neg_lo:[0,0,1] neg_hi:[0,0,1]
	v_and_b32_e32 v91, 0xffff0000, v77
	s_waitcnt lgkmcnt(0)
	v_pk_fma_f32 v[82:83], v[88:89], v[82:83], v[86:87]
	v_lshlrev_b32_e32 v88, 16, v73
	v_and_b32_e32 v89, 0xffff0000, v73
	v_lshlrev_b32_e32 v86, 16, v69
	v_and_b32_e32 v87, 0xffff0000, v69
	v_pk_add_f32 v[88:89], v[88:89], v[90:91]
	v_cvt_pk_bf16_f32 v78, v78, v79
	v_pk_fma_f32 v[88:89], v[88:89], 0.5, v[86:87] op_sel_hi:[1,0,1] neg_lo:[0,0,1] neg_hi:[0,0,1]
	v_cvt_pk_bf16_f32 v79, v80, v81
	v_pk_fma_f32 v[84:85], v[88:89], v[84:85], v[86:87]
	v_cvt_pk_bf16_f32 v80, v82, v83
	v_cvt_pk_bf16_f32 v81, v84, v85
	ds_write_b128 v186, v[78:81] offset:62464
	s_waitcnt lgkmcnt(0)
	s_barrier
	ds_read_b128 v[78:81], v159 offset:57856
	ds_read_b128 v[82:85], v159 offset:57920
	s_waitcnt lgkmcnt(1)
	v_mfma_f32_16x16x32_bf16 v[78:81], v[78:81], v[2:5], 0
	ds_read_b128 v[86:89], v159 offset:62464
	s_waitcnt lgkmcnt(1)
	v_mfma_f32_16x16x32_bf16 v[82:85], v[82:85], v[6:9], v[78:81]
	s_nop 4
	ds_read_b128 v[78:81], v159 offset:62528
	s_waitcnt lgkmcnt(1)
	v_mfma_f32_16x16x32_bf16 v[86:89], v[86:89], v[10:13], 0
	v_add_f32_e32 v1, v173, v82
	v_mul_f32_e32 v1, 0xbfb8aa3b, v1
	v_exp_f32_e32 v1, v1
	s_waitcnt lgkmcnt(0)
	v_mfma_f32_16x16x32_bf16 v[78:81], v[78:81], v[14:17], v[86:89]
	ds_read2st64_b32 v[106:107], v193 offset1:64
	ds_read_b32 v108, v193 offset:24576
	ds_read2st64_b32 v[110:111], v195 offset1:64
	ds_read_b32 v109, v195 offset:24576
	ds_read2st64_b32 v[112:113], v196 offset1:64
	ds_read_b32 v114, v196 offset:24576
	ds_read2st64_b32 v[116:117], v197 offset1:64
	ds_read_b32 v115, v197 offset:24576
	v_add_f32_e32 v1, 1.0, v1
	s_nop 4
	s_nop 1
	v_add_f32_e32 v78, v175, v78
	v_mul_f32_e32 v78, 0xbfb8aa3b, v78
	v_exp_f32_e32 v78, v78
	s_nop 4
	v_add_f32_e32 v78, 1.0, v78
	v_rcp_f32_e32 v82, v1
	s_nop 0
	v_mul_f32_e32 v1, s16, v82
	v_mul_f32_e32 v1, 0x3fb8aa3b, v1
	v_rcp_f32_e32 v78, v78
	s_nop 0
	s_nop 2
	v_exp_f32_e32 v1, v1
	s_waitcnt lgkmcnt(1)
	v_mul_f32_e32 v87, v107, v78
	v_add_f32_e32 v78, -1.0, v78
	v_fma_f32 v78, v176, v78, 1.0
	s_waitcnt lgkmcnt(0)
	v_mul_f32_e32 v78, v108, v78
	ds_write2st64_b32 v193, v78, v1 offset0:96 offset1:128
	v_mul_f32_e32 v1, v106, v78
	v_mul_f32_e32 v78, v177, v1
	ds_write_b32 v193, v87 offset:40960
	s_nop 0
	v_mov_b32_dpp v78, v78 quad_perm:[1,0,3,2] row_mask:0xf bank_mask:0xf bound_ctrl:1
	v_fmac_f32_e32 v78, v177, v1
	s_nop 1
	v_add_f32_dpp v1, v78, v78 quad_perm:[2,3,0,1] row_mask:0xf bank_mask:0xf bound_ctrl:1
	s_nop 1
	v_add_f32_dpp v1, v1, v1 row_half_mirror row_mask:0xf bank_mask:0xf bound_ctrl:1
	s_nop 1
	v_mov_b32_dpp v78, v1 row_mirror row_mask:0xf bank_mask:0xf bound_ctrl:1
	s_and_saveexec_b64 s[6:7], s[40:41]
	v_add_f32_e32 v1, v1, v78
	ds_write_b32 v194, v1 offset:57344
	s_or_b64 exec, exec, s[6:7]
	v_add_f32_e32 v1, v173, v83
	v_mul_f32_e32 v1, 0xbfb8aa3b, v1
	v_exp_f32_e32 v1, v1
	v_add_f32_e32 v78, v175, v79
	v_mul_f32_e32 v78, 0xbfb8aa3b, v78
	v_exp_f32_e32 v78, v78
	v_add_f32_e32 v1, 1.0, v1
	s_nop 3
	v_add_f32_e32 v82, 1.0, v78
	v_rcp_f32_e32 v79, v1
	s_nop 0
	v_mul_f32_e32 v1, s16, v79
	v_mul_f32_e32 v1, 0x3fb8aa3b, v1
	v_exp_f32_e32 v1, v1
	v_rcp_f32_e32 v82, v82
	s_nop 0
	s_waitcnt lgkmcnt(1)
	v_mul_f32_e32 v79, v82, v111
	ds_write_b32 v195, v79 offset:40960
	v_add_f32_e32 v79, -1.0, v82
	v_fma_f32 v79, v176, v79, 1.0
	s_waitcnt lgkmcnt(1)
	v_mul_f32_e32 v79, v79, v109
	ds_write2st64_b32 v195, v79, v1 offset0:96 offset1:128
	v_mul_f32_e32 v1, v79, v110
	v_mul_f32_e32 v78, v177, v1
	s_nop 1
	v_mov_b32_dpp v78, v78 quad_perm:[1,0,3,2] row_mask:0xf bank_mask:0xf bound_ctrl:1
	v_fmac_f32_e32 v78, v177, v1
	s_nop 1
	v_add_f32_dpp v1, v78, v78 quad_perm:[2,3,0,1] row_mask:0xf bank_mask:0xf bound_ctrl:1
	s_nop 1
	v_add_f32_dpp v1, v1, v1 row_half_mirror row_mask:0xf bank_mask:0xf bound_ctrl:1
	s_nop 1
	v_mov_b32_dpp v78, v1 row_mirror row_mask:0xf bank_mask:0xf bound_ctrl:1
	s_and_saveexec_b64 s[6:7], s[40:41]
	v_add_f32_e32 v1, v1, v78
	ds_write_b32 v194, v1 offset:57348
	s_or_b64 exec, exec, s[6:7]
	v_add_f32_e32 v1, v173, v84
	v_mul_f32_e32 v1, 0xbfb8aa3b, v1
	v_exp_f32_e32 v1, v1
	v_add_f32_e32 v78, v175, v80
	v_mul_f32_e32 v78, 0xbfb8aa3b, v78
	v_exp_f32_e32 v78, v78
	v_add_f32_e32 v1, 1.0, v1
	s_nop 3
	v_add_f32_e32 v80, 1.0, v78
	v_rcp_f32_e32 v79, v1
	s_nop 0
	v_mul_f32_e32 v1, s16, v79
	v_mul_f32_e32 v1, 0x3fb8aa3b, v1
	v_exp_f32_e32 v1, v1
	v_rcp_f32_e32 v80, v80
	s_nop 0
	s_waitcnt lgkmcnt(1)
	v_mul_f32_e32 v79, v80, v113
	ds_write_b32 v196, v79 offset:40960
	v_add_f32_e32 v79, -1.0, v80
	v_fma_f32 v79, v176, v79, 1.0
	s_waitcnt lgkmcnt(1)
	v_mul_f32_e32 v79, v79, v114
	ds_write2st64_b32 v196, v79, v1 offset0:96 offset1:128
	v_mul_f32_e32 v1, v79, v112
	v_mul_f32_e32 v78, v177, v1
	s_nop 1
	v_mov_b32_dpp v78, v78 quad_perm:[1,0,3,2] row_mask:0xf bank_mask:0xf bound_ctrl:1
	v_fmac_f32_e32 v78, v177, v1
	s_nop 1
	v_add_f32_dpp v1, v78, v78 quad_perm:[2,3,0,1] row_mask:0xf bank_mask:0xf bound_ctrl:1
	s_nop 1
	v_add_f32_dpp v1, v1, v1 row_half_mirror row_mask:0xf bank_mask:0xf bound_ctrl:1
	s_nop 1
	v_mov_b32_dpp v78, v1 row_mirror row_mask:0xf bank_mask:0xf bound_ctrl:1
	s_and_saveexec_b64 s[6:7], s[40:41]
	v_add_f32_e32 v1, v1, v78
	ds_write_b32 v194, v1 offset:57352
	s_or_b64 exec, exec, s[6:7]
	v_add_f32_e32 v1, v173, v85
	v_mul_f32_e32 v1, 0xbfb8aa3b, v1
	v_exp_f32_e32 v1, v1
	v_add_f32_e32 v78, v175, v81
	v_mul_f32_e32 v78, 0xbfb8aa3b, v78
	v_exp_f32_e32 v78, v78
	v_add_f32_e32 v1, 1.0, v1
	s_nop 3
	v_add_f32_e32 v80, 1.0, v78
	v_rcp_f32_e32 v79, v1
	s_nop 0
	v_mul_f32_e32 v1, s16, v79
	v_mul_f32_e32 v1, 0x3fb8aa3b, v1
	v_exp_f32_e32 v1, v1
	v_rcp_f32_e32 v80, v80
	s_nop 0
	s_waitcnt lgkmcnt(1)
	v_mul_f32_e32 v79, v80, v117
	ds_write_b32 v197, v79 offset:40960
	v_add_f32_e32 v79, -1.0, v80
	v_fma_f32 v79, v176, v79, 1.0
	s_waitcnt lgkmcnt(1)
	v_mul_f32_e32 v79, v79, v115
	ds_write2st64_b32 v197, v79, v1 offset0:96 offset1:128
	v_mul_f32_e32 v1, v79, v116
	v_mul_f32_e32 v78, v177, v1
	s_nop 1
	v_mov_b32_dpp v78, v78 quad_perm:[1,0,3,2] row_mask:0xf bank_mask:0xf bound_ctrl:1
	v_fmac_f32_e32 v78, v177, v1
	s_nop 1
	v_add_f32_dpp v1, v78, v78 quad_perm:[2,3,0,1] row_mask:0xf bank_mask:0xf bound_ctrl:1
	s_nop 1
	v_add_f32_dpp v1, v1, v1 row_half_mirror row_mask:0xf bank_mask:0xf bound_ctrl:1
	s_nop 1
	v_mov_b32_dpp v78, v1 row_mirror row_mask:0xf bank_mask:0xf bound_ctrl:1
	s_and_saveexec_b64 s[6:7], s[40:41]
	v_add_f32_e32 v1, v1, v78
	ds_write_b32 v194, v1 offset:57356
	s_or_b64 exec, exec, s[6:7]
	ds_read_b128 v[82:85], v159 offset:64768
	ds_read_b128 v[78:81], v159 offset:60160
	s_waitcnt lgkmcnt(1)
	v_mfma_f32_16x16x32_bf16 v[86:89], v[82:85], v[10:13], 0
	ds_read_b128 v[82:85], v159 offset:60224
	s_waitcnt lgkmcnt(1)
	v_mfma_f32_16x16x32_bf16 v[78:81], v[78:81], v[2:5], 0
	s_waitcnt lgkmcnt(0)
	v_mfma_f32_16x16x32_bf16 v[82:85], v[82:85], v[6:9], v[78:81]
	s_nop 5
	ds_read_b128 v[78:81], v159 offset:64832
	s_nop 0
	v_add_f32_e32 v1, v173, v82
	v_mul_f32_e32 v1, 0xbfb8aa3b, v1
	v_exp_f32_e32 v1, v1
	s_waitcnt lgkmcnt(0)
	v_mfma_f32_16x16x32_bf16 v[78:81], v[78:81], v[14:17], v[86:89]
	ds_read2st64_b32 v[106:107], v198 offset1:64
	ds_read_b32 v108, v198 offset:24576
	ds_read2st64_b32 v[110:111], v199 offset1:64
	ds_read_b32 v109, v199 offset:24576
	ds_read2st64_b32 v[112:113], v200 offset1:64
	ds_read_b32 v114, v200 offset:24576
	ds_read2st64_b32 v[116:117], v201 offset1:64
	ds_read_b32 v115, v201 offset:24576
	v_add_f32_e32 v1, 1.0, v1
	s_nop 5
	s_nop 0
	v_add_f32_e32 v78, v175, v78
	v_mul_f32_e32 v78, 0xbfb8aa3b, v78
	v_exp_f32_e32 v78, v78
	s_nop 1
	v_add_f32_e32 v78, 1.0, v78
	v_rcp_f32_e32 v82, v1
	s_nop 0
	v_mul_f32_e32 v1, s16, v82
	v_rcp_f32_e32 v78, v78
	s_nop 0
	v_mul_f32_e32 v1, 0x3fb8aa3b, v1
	v_exp_f32_e32 v1, v1
	s_waitcnt lgkmcnt(1)
	v_mul_f32_e32 v87, v107, v78
	v_add_f32_e32 v78, -1.0, v78
	v_fma_f32 v78, v176, v78, 1.0
	s_waitcnt lgkmcnt(0)
	v_mul_f32_e32 v78, v108, v78
	ds_write2st64_b32 v198, v78, v1 offset0:96 offset1:128
	v_mul_f32_e32 v1, v106, v78
	v_mul_f32_e32 v78, v177, v1
	ds_write_b32 v198, v87 offset:40960
	s_nop 0
	v_mov_b32_dpp v78, v78 quad_perm:[1,0,3,2] row_mask:0xf bank_mask:0xf bound_ctrl:1
	v_fmac_f32_e32 v78, v177, v1
	s_nop 1
	v_add_f32_dpp v1, v78, v78 quad_perm:[2,3,0,1] row_mask:0xf bank_mask:0xf bound_ctrl:1
	s_nop 1
	v_add_f32_dpp v1, v1, v1 row_half_mirror row_mask:0xf bank_mask:0xf bound_ctrl:1
	s_nop 1
	v_mov_b32_dpp v78, v1 row_mirror row_mask:0xf bank_mask:0xf bound_ctrl:1
	s_and_saveexec_b64 s[6:7], s[40:41]
	v_add_f32_e32 v1, v1, v78
	ds_write_b32 v194, v1 offset:57408
	s_or_b64 exec, exec, s[6:7]
	v_add_f32_e32 v1, v173, v83
	v_mul_f32_e32 v1, 0xbfb8aa3b, v1
	v_exp_f32_e32 v1, v1
	v_add_f32_e32 v78, v175, v79
	v_mul_f32_e32 v78, 0xbfb8aa3b, v78
	v_exp_f32_e32 v78, v78
	v_add_f32_e32 v1, 1.0, v1
	s_nop 3
	v_add_f32_e32 v82, 1.0, v78
	v_rcp_f32_e32 v79, v1
	s_nop 0
	v_mul_f32_e32 v1, s16, v79
	v_mul_f32_e32 v1, 0x3fb8aa3b, v1
	v_exp_f32_e32 v1, v1
	v_rcp_f32_e32 v82, v82
	s_nop 0
	s_waitcnt lgkmcnt(1)
	v_mul_f32_e32 v79, v82, v111
	ds_write_b32 v199, v79 offset:40960
	v_add_f32_e32 v79, -1.0, v82
	v_fma_f32 v79, v176, v79, 1.0
	s_waitcnt lgkmcnt(1)
	v_mul_f32_e32 v79, v79, v109
	ds_write2st64_b32 v199, v79, v1 offset0:96 offset1:128
	v_mul_f32_e32 v1, v79, v110
	v_mul_f32_e32 v78, v177, v1
	s_nop 1
	v_mov_b32_dpp v78, v78 quad_perm:[1,0,3,2] row_mask:0xf bank_mask:0xf bound_ctrl:1
	v_fmac_f32_e32 v78, v177, v1
	s_nop 1
	v_add_f32_dpp v1, v78, v78 quad_perm:[2,3,0,1] row_mask:0xf bank_mask:0xf bound_ctrl:1
	s_nop 1
	v_add_f32_dpp v1, v1, v1 row_half_mirror row_mask:0xf bank_mask:0xf bound_ctrl:1
	s_nop 1
	v_mov_b32_dpp v78, v1 row_mirror row_mask:0xf bank_mask:0xf bound_ctrl:1
	s_and_saveexec_b64 s[6:7], s[40:41]
	v_add_f32_e32 v1, v1, v78
	ds_write_b32 v194, v1 offset:57412
	s_or_b64 exec, exec, s[6:7]
	v_add_f32_e32 v1, v173, v84
	v_mul_f32_e32 v1, 0xbfb8aa3b, v1
	v_exp_f32_e32 v1, v1
	v_add_f32_e32 v78, v175, v80
	v_mul_f32_e32 v78, 0xbfb8aa3b, v78
	v_exp_f32_e32 v78, v78
	v_add_f32_e32 v1, 1.0, v1
	s_nop 3
	v_add_f32_e32 v80, 1.0, v78
	v_rcp_f32_e32 v79, v1
	s_nop 0
	v_mul_f32_e32 v1, s16, v79
	v_mul_f32_e32 v1, 0x3fb8aa3b, v1
	v_exp_f32_e32 v1, v1
	v_rcp_f32_e32 v80, v80
	s_nop 0
	s_waitcnt lgkmcnt(1)
	v_mul_f32_e32 v79, v80, v113
	ds_write_b32 v200, v79 offset:40960
	v_add_f32_e32 v79, -1.0, v80
	v_fma_f32 v79, v176, v79, 1.0
	s_waitcnt lgkmcnt(1)
	v_mul_f32_e32 v79, v79, v114
	ds_write2st64_b32 v200, v79, v1 offset0:96 offset1:128
	v_mul_f32_e32 v1, v79, v112
	v_mul_f32_e32 v78, v177, v1
	s_nop 1
	v_mov_b32_dpp v78, v78 quad_perm:[1,0,3,2] row_mask:0xf bank_mask:0xf bound_ctrl:1
	v_fmac_f32_e32 v78, v177, v1
	s_nop 1
	v_add_f32_dpp v1, v78, v78 quad_perm:[2,3,0,1] row_mask:0xf bank_mask:0xf bound_ctrl:1
	s_nop 1
	v_add_f32_dpp v1, v1, v1 row_half_mirror row_mask:0xf bank_mask:0xf bound_ctrl:1
	s_nop 1
	v_mov_b32_dpp v78, v1 row_mirror row_mask:0xf bank_mask:0xf bound_ctrl:1
	s_and_saveexec_b64 s[6:7], s[40:41]
	v_add_f32_e32 v1, v1, v78
	ds_write_b32 v194, v1 offset:57416
	s_or_b64 exec, exec, s[6:7]
	v_add_f32_e32 v1, v173, v85
	v_mul_f32_e32 v1, 0xbfb8aa3b, v1
	v_exp_f32_e32 v1, v1
	v_add_f32_e32 v78, v175, v81
	v_mul_f32_e32 v78, 0xbfb8aa3b, v78
	v_exp_f32_e32 v78, v78
	v_add_f32_e32 v1, 1.0, v1
	s_nop 3
	v_add_f32_e32 v80, 1.0, v78
	v_rcp_f32_e32 v79, v1
	s_nop 0
	v_mul_f32_e32 v1, s16, v79
	v_mul_f32_e32 v1, 0x3fb8aa3b, v1
	v_exp_f32_e32 v1, v1
	v_rcp_f32_e32 v80, v80
	s_nop 0
	s_waitcnt lgkmcnt(1)
	v_mul_f32_e32 v79, v80, v117
	ds_write_b32 v201, v79 offset:40960
	v_add_f32_e32 v79, -1.0, v80
	v_fma_f32 v79, v176, v79, 1.0
	s_waitcnt lgkmcnt(1)
	v_mul_f32_e32 v79, v79, v115
	ds_write2st64_b32 v201, v79, v1 offset0:96 offset1:128
	v_mul_f32_e32 v1, v79, v116
	v_mul_f32_e32 v78, v177, v1
	s_nop 1
	v_mov_b32_dpp v78, v78 quad_perm:[1,0,3,2] row_mask:0xf bank_mask:0xf bound_ctrl:1
	v_fmac_f32_e32 v78, v177, v1
	s_nop 1
	v_add_f32_dpp v1, v78, v78 quad_perm:[2,3,0,1] row_mask:0xf bank_mask:0xf bound_ctrl:1
	s_nop 1
	v_add_f32_dpp v1, v1, v1 row_half_mirror row_mask:0xf bank_mask:0xf bound_ctrl:1
	s_nop 1
	v_mov_b32_dpp v78, v1 row_mirror row_mask:0xf bank_mask:0xf bound_ctrl:1
	s_and_saveexec_b64 s[6:7], s[40:41]
	v_add_f32_e32 v1, v1, v78
	ds_write_b32 v194, v1 offset:57420
	s_or_b64 exec, exec, s[6:7]
	s_add_i32 s10, s1, 1
	s_cmpk_eq_i32 s1, 0x47
	s_cbranch_scc1 .LBB0_682
	s_add_i32 s11, s1, -7
	s_cmp_gt_u32 s1, 6
	s_cselect_b64 s[6:7], -1, 0
	s_and_b64 s[12:13], s[6:7], exec
	s_cselect_b32 s11, s11, s10
	s_cselect_b32 s12, 0x100, 0
	s_cselect_b32 s13, 63, 7
	s_add_i32 s14, s12, s79
	s_sub_i32 s15, s13, s11
	s_and_b64 s[12:13], s[50:51], exec
	s_cselect_b32 s11, s11, s15
	v_lshl_add_u32 v1, s11, 5, v178
	v_add_u32_e32 v18, s14, v1
	v_mad_i64_i32 v[54:55], s[12:13], v18, s17, v[160:161]
	s_mov_b32 s53, s9
	v_lshl_add_u64 v[56:57], v[54:55], 0, s[52:53]
	global_load_dwordx4 v[18:21], v[56:57], off offset:2880
	v_mov_b32_e32 v28, v0
	v_mov_b32_e32 v29, v0
	v_cmp_lt_i32_e64 s[46:47], 0, v1
	v_mov_b64_e32 v[24:25], v[28:29]
	v_mov_b64_e32 v[22:23], v[28:29]
	s_and_saveexec_b64 s[12:13], s[46:47]
	s_cbranch_execz .LBB0_663
	v_add_co_u32_e32 v22, vcc, 0xfffff000, v56
	s_nop 1
	v_addc_co_u32_e32 v23, vcc, -1, v57, vcc
	global_load_dwordx4 v[22:25], v[22:23], off offset:-3008
